# gdn_scan stager de-serialisation: straight-line issue of the 11 per-chunk LDS-DMA loads (no spilled-SGPR readlanes, no per-piece predicate branches; LDS slot = previous + 6 KiB)
# speedup vs baseline: 1.0184x; 1.0184x over previous
.LBB0_531:
	s_andn2_b64 vcc, exec, s[60:61]
	s_cbranch_vccnz .LBB0_546
	s_cmp_eq_u32 s87, 63
	s_cbranch_scc1 .LBB0_545
	s_add_i32 s60, s87, 1
	s_bitcmp1_b32 s60, 0
	s_cselect_b32 s52, 0xfc00, 0
	s_add_i32 s61, s52, 0
	v_readlane_b32 s98, v255, 37
	s_lshl_b32 s100, s60, 16
	s_mov_b32 s101, 0
	s_nop 0
	s_add_i32 s98, s98, s61
	v_lshl_add_u64 v[18:19], v[94:95], 0, s[100:101]
	v_lshl_add_u64 v[176:177], v[96:97], 0, s[100:101]
	v_lshl_add_u64 v[178:179], v[98:99], 0, s[100:101]
	v_lshl_add_u64 v[180:181], v[100:101], 0, s[100:101]
	s_mov_b32 m0, s98
	s_nop 0
	global_load_lds_dwordx4 v[18:19], off
	s_add_i32 m0, s98, 0x1800
	s_nop 0
	global_load_lds_dwordx4 v[176:177], off
	s_add_i32 m0, s98, 0x3000
	s_nop 0
	global_load_lds_dwordx4 v[178:179], off
	s_add_i32 m0, s98, 0x4800
	s_nop 0
	global_load_lds_dwordx4 v[180:181], off
	v_lshl_add_u64 v[18:19], v[102:103], 0, s[100:101]
	v_lshl_add_u64 v[176:177], v[104:105], 0, s[100:101]
	v_lshl_add_u64 v[178:179], v[106:107], 0, s[100:101]
	v_lshl_add_u64 v[180:181], v[108:109], 0, s[100:101]
	s_add_i32 m0, s98, 0x6000
	s_nop 0
	global_load_lds_dwordx4 v[18:19], off
	s_add_i32 m0, s98, 0x7800
	s_nop 0
	global_load_lds_dwordx4 v[176:177], off
	s_add_i32 m0, s98, 0x9000
	s_nop 0
	global_load_lds_dwordx4 v[178:179], off
	s_add_i32 m0, s98, 0xa800
	s_nop 0
	global_load_lds_dwordx4 v[180:181], off
	s_lshl_b32 s52, s60, s84
	s_nop 0
	v_lshl_add_u64 v[18:19], v[110:111], 0, s[52:53]
	s_lshl_b32 s52, s60, s5
	s_nop 0
	v_lshl_add_u64 v[176:177], v[112:113], 0, s[52:53]
	s_add_i32 m0, s98, 0xc000
	s_nop 0
	global_load_lds_dwordx4 v[18:19], off
	s_add_i32 m0, s98, 0xd800
	s_nop 0
	global_load_lds_dwordx4 v[176:177], off
	s_andn2_b64 vcc, exec, s[8:9]
	s_cbranch_vccnz .LBB0_545
	s_lshl_b32 s52, s60, s13
	s_nop 0
	v_lshl_add_u64 v[18:19], v[114:115], 0, s[52:53]
	s_add_i32 m0, s98, 0xf000
	s_nop 0
	global_load_lds_dwordx4 v[18:19], off

.LBB0_554:
	s_andn2_b64 vcc, exec, s[60:61]
	s_cbranch_vccz .LBB0_521
	v_mov_b64_e32 v[70:71], v[46:47]
	v_mov_b64_e32 v[66:67], v[38:39]
	v_mov_b64_e32 v[74:75], v[42:43]
	v_mov_b64_e32 v[78:79], v[50:51]
	v_mov_b64_e32 v[68:69], v[44:45]
	v_mov_b64_e32 v[64:65], v[36:37]
	v_mov_b64_e32 v[72:73], v[40:41]
	v_mov_b64_e32 v[76:77], v[48:49]
	s_branch .LBB0_522
.LBB0_566:
	s_waitcnt vmcnt(0)
	v_mov_b32_e32 v0, v228
	s_barrier
	s_nop 0
	v_cmp_eq_u32_e32 vcc, 0, v0
	s_and_saveexec_b64 s[8:9], vcc
	v_readlane_b32 s19, v255, 27
	s_cbranch_execz .LBB0_568
	v_readlane_b32 s4, v255, 18
	v_readlane_b32 s5, v255, 19
	s_and_b32 s2, s4, 7
	s_lshl_b32 s2, s2, 4
	s_lshr_b32 s4, s4, 3
	s_or_b32 s4, s4, s2
	s_ashr_i32 s4, s4, 3
	s_ashr_i32 s5, s4, 31
	s_lshl_b64 s[4:5], s[4:5], 2
	s_add_u32 s4, s19, s4
	v_readlane_b32 s2, v255, 26
	s_addc_u32 s5, s2, s5
	buffer_wbl2 sc1
	s_waitcnt vmcnt(0)
	v_mov_b64_e32 v[0:1], s[4:5]
	global_atomic_add v[0:1], v230, off
